# attention O stores nt instead of write-through
# speedup vs baseline: 1.0076x; 1.0028x over previous
.LBB0_303:
	s_cmpk_gt_u32 s65, 0xff
	s_waitcnt lgkmcnt(0)
	s_barrier
	s_cbranch_scc1 .LBB0_275
	s_mulk_i32 s64, 0x2200
	s_add_i32 s34, s64, 0
	s_add_i32 s34, s34, 0x10000
	ds_read2st64_b32 v[130:131], v71 offset1:1
	ds_read2st64_b32 v[132:133], v71 offset0:2 offset1:3
	ds_read2st64_b32 v[134:135], v71 offset0:4 offset1:5
	ds_read2st64_b32 v[136:137], v71 offset0:6 offset1:7
	ds_read2st64_b32 v[138:139], v71 offset0:8 offset1:9
	ds_read2st64_b32 v[140:141], v71 offset0:10 offset1:11
	ds_read2st64_b32 v[142:143], v71 offset0:12 offset1:13
	ds_read2st64_b32 v[144:145], v71 offset0:14 offset1:15
	ds_read2st64_b32 v[146:147], v71 offset0:16 offset1:17
	ds_read2st64_b32 v[148:149], v71 offset0:18 offset1:19
	ds_read2st64_b32 v[150:151], v71 offset0:20 offset1:21
	ds_read2st64_b32 v[172:173], v71 offset0:22 offset1:23
	ds_read2st64_b32 v[174:175], v71 offset0:24 offset1:25
	ds_read2st64_b32 v[176:177], v71 offset0:26 offset1:27
	ds_read2st64_b32 v[178:179], v71 offset0:28 offset1:29
	ds_read2st64_b32 v[180:181], v71 offset0:30 offset1:31
	ds_read2st64_b32 v[182:183], v71 offset0:32 offset1:33
	ds_read2st64_b32 v[184:185], v71 offset0:34 offset1:35
	ds_read2st64_b32 v[186:187], v71 offset0:36 offset1:37
	ds_read2st64_b32 v[188:189], v71 offset0:38 offset1:39
	ds_read2st64_b32 v[190:191], v71 offset0:40 offset1:41
	ds_read2st64_b32 v[192:193], v71 offset0:42 offset1:43
	ds_read2st64_b32 v[194:195], v71 offset0:44 offset1:45
	ds_read2st64_b32 v[196:197], v71 offset0:46 offset1:47
	ds_read2st64_b32 v[198:199], v71 offset0:48 offset1:49
	ds_read2st64_b32 v[200:201], v71 offset0:50 offset1:51
	ds_read2st64_b32 v[202:203], v71 offset0:52 offset1:53
	ds_read2st64_b32 v[204:205], v71 offset0:54 offset1:55
	ds_read2st64_b32 v[206:207], v71 offset0:56 offset1:57
	ds_read2st64_b32 v[208:209], v71 offset0:58 offset1:59
	ds_read2st64_b32 v[210:211], v71 offset0:60 offset1:61
	ds_read2st64_b32 v[212:213], v71 offset0:62 offset1:63
	s_waitcnt lgkmcnt(15)
	v_sub_f32_e32 v60, v72, v130
	v_sub_f32_e32 v55, v0, v131
	v_sub_f32_e32 v52, v73, v132
	v_sub_f32_e32 v47, v74, v133
	v_sub_f32_e32 v44, v3, v134
	v_sub_f32_e32 v39, v36, v135
	v_sub_f32_e32 v28, v23, v138
	v_sub_f32_e32 v23, v38, v139
	v_sub_f32_e32 v36, v20, v136
	v_sub_f32_e32 v31, v6, v137
	v_sub_f32_e32 v20, v41, v140
	v_sub_f32_e32 v15, v26, v141
	v_sub_f32_e32 v12, v54, v142
	v_sub_f32_e32 v6, v77, v143
	v_sub_f32_e32 v3, v57, v144
	v_sub_f32_e32 v0, v14, v145
	v_sub_f32_e32 v62, v68, v146
	v_sub_f32_e32 v57, v49, v147
	v_sub_f32_e32 v54, v1, v148
	v_sub_f32_e32 v49, v18, v149
	v_sub_f32_e32 v46, v34, v150
	v_sub_f32_e32 v41, v51, v151
	v_sub_f32_e32 v38, v5, v172
	v_sub_f32_e32 v34, v22, v173
	v_sub_f32_e32 v30, v40, v174
	v_sub_f32_e32 v26, v56, v175
	v_sub_f32_e32 v22, v75, v176
	v_sub_f32_e32 v18, v10, v177
	v_sub_f32_e32 v14, v27, v178
	v_sub_f32_e32 v10, v59, v179
	v_sub_f32_e32 v5, v43, v180
	v_sub_f32_e32 v1, v76, v181
	v_sub_f32_e32 v74, v16, v182
	v_sub_f32_e32 v59, v32, v183
	s_waitcnt lgkmcnt(14)
	v_sub_f32_e32 v56, v48, v184
	v_sub_f32_e32 v51, v2, v185
	s_waitcnt lgkmcnt(13)
	v_sub_f32_e32 v48, v19, v186
	v_sub_f32_e32 v43, v53, v187
	s_waitcnt lgkmcnt(12)
	v_sub_f32_e32 v40, v35, v188
	v_sub_f32_e32 v35, v69, v189
	s_waitcnt lgkmcnt(11)
	v_sub_f32_e32 v32, v7, v190
	v_sub_f32_e32 v27, v24, v191
	s_waitcnt lgkmcnt(10)
	v_sub_f32_e32 v24, v42, v192
	v_sub_f32_e32 v19, v58, v193
	s_waitcnt lgkmcnt(9)
	v_sub_f32_e32 v16, v11, v194
	v_sub_f32_e32 v11, v29, v195
	s_waitcnt lgkmcnt(8)
	v_sub_f32_e32 v7, v45, v196
	v_sub_f32_e32 v2, v61, v197
	s_waitcnt lgkmcnt(7)
	v_sub_f32_e32 v72, v64, v198
	v_sub_f32_e32 v61, v17, v199
	s_waitcnt lgkmcnt(6)
	v_sub_f32_e32 v58, v33, v200
	v_sub_f32_e32 v53, v50, v201
	s_waitcnt lgkmcnt(5)
	v_sub_f32_e32 v50, v4, v202
	v_sub_f32_e32 v45, v21, v203
	s_waitcnt lgkmcnt(4)
	v_sub_f32_e32 v42, v37, v204
	v_sub_f32_e32 v37, v65, v205
	s_waitcnt lgkmcnt(3)
	v_sub_f32_e32 v33, v8, v206
	v_sub_f32_e32 v29, v9, v207
	s_waitcnt lgkmcnt(2)
	v_sub_f32_e32 v25, v25, v208
	v_sub_f32_e32 v21, v66, v209
	s_waitcnt lgkmcnt(0)
	v_sub_f32_e32 v4, v63, v213
	v_sub_f32_e32 v13, v13, v211
	v_sub_f32_e32 v9, v70, v212
	v_sub_f32_e32 v17, v67, v210
	s_waitcnt lgkmcnt(0)
	v_mul_f32_e32 v130, v62, v62
	v_fmac_f32_e32 v130, v60, v60
	v_fmac_f32_e32 v130, v74, v74
	v_fmac_f32_e32 v130, v72, v72
	v_mul_f32_e32 v131, v57, v57
	v_fmac_f32_e32 v131, v55, v55
	v_fmac_f32_e32 v131, v59, v59
	v_fmac_f32_e32 v131, v61, v61
	v_mul_f32_e32 v132, v54, v54
	v_fmac_f32_e32 v132, v52, v52
	v_fmac_f32_e32 v132, v56, v56
	v_fmac_f32_e32 v132, v58, v58
	v_mul_f32_e32 v133, v49, v49
	v_fmac_f32_e32 v133, v47, v47
	v_fmac_f32_e32 v133, v51, v51
	v_fmac_f32_e32 v133, v53, v53
	v_mul_f32_e32 v134, v46, v46
	v_fmac_f32_e32 v134, v44, v44
	v_fmac_f32_e32 v134, v48, v48
	v_fmac_f32_e32 v134, v50, v50
	v_mul_f32_e32 v135, v41, v41
	v_fmac_f32_e32 v135, v39, v39
	v_fmac_f32_e32 v135, v43, v43
	v_fmac_f32_e32 v135, v45, v45
	v_mul_f32_e32 v136, v38, v38
	v_fmac_f32_e32 v136, v36, v36
	v_fmac_f32_e32 v136, v40, v40
	v_fmac_f32_e32 v136, v42, v42
	v_mul_f32_e32 v137, v34, v34
	v_fmac_f32_e32 v137, v31, v31
	v_fmac_f32_e32 v137, v35, v35
	v_fmac_f32_e32 v137, v37, v37
	v_mul_f32_e32 v138, v30, v30
	v_fmac_f32_e32 v138, v28, v28
	v_fmac_f32_e32 v138, v32, v32
	v_fmac_f32_e32 v138, v33, v33
	v_mul_f32_e32 v139, v26, v26
	v_fmac_f32_e32 v139, v23, v23
	v_fmac_f32_e32 v139, v27, v27
	v_fmac_f32_e32 v139, v29, v29
	v_mul_f32_e32 v140, v22, v22
	v_fmac_f32_e32 v140, v20, v20
	v_fmac_f32_e32 v140, v24, v24
	v_fmac_f32_e32 v140, v25, v25
	v_mul_f32_e32 v141, v18, v18
	v_fmac_f32_e32 v141, v15, v15
	v_fmac_f32_e32 v141, v19, v19
	v_fmac_f32_e32 v141, v21, v21
	v_mul_f32_e32 v142, v14, v14
	v_fmac_f32_e32 v142, v12, v12
	v_fmac_f32_e32 v142, v16, v16
	v_fmac_f32_e32 v142, v17, v17
	v_mul_f32_e32 v143, v10, v10
	v_fmac_f32_e32 v143, v6, v6
	v_fmac_f32_e32 v143, v11, v11
	v_fmac_f32_e32 v143, v13, v13
	v_mul_f32_e32 v144, v5, v5
	v_fmac_f32_e32 v144, v3, v3
	v_fmac_f32_e32 v144, v7, v7
	v_fmac_f32_e32 v144, v9, v9
	v_mul_f32_e32 v145, v1, v1
	v_fmac_f32_e32 v145, v0, v0
	v_fmac_f32_e32 v145, v2, v2
	v_fmac_f32_e32 v145, v4, v4
	ds_bpermute_b32 v146, v161, v130
	ds_bpermute_b32 v147, v161, v131
	ds_bpermute_b32 v148, v161, v132
	ds_bpermute_b32 v149, v161, v133
	ds_bpermute_b32 v150, v161, v134
	ds_bpermute_b32 v151, v161, v135
	ds_bpermute_b32 v172, v161, v136
	ds_bpermute_b32 v173, v161, v137
	ds_bpermute_b32 v174, v161, v138
	ds_bpermute_b32 v175, v161, v139
	ds_bpermute_b32 v176, v161, v140
	ds_bpermute_b32 v177, v161, v141
	ds_bpermute_b32 v178, v161, v142
	ds_bpermute_b32 v179, v161, v143
	ds_bpermute_b32 v180, v161, v144
	ds_bpermute_b32 v181, v161, v145
	s_waitcnt lgkmcnt(15)
	v_add_f32_e32 v130, v130, v146
	s_waitcnt lgkmcnt(14)
	v_add_f32_e32 v131, v131, v147
	s_waitcnt lgkmcnt(13)
	v_add_f32_e32 v132, v132, v148
	s_waitcnt lgkmcnt(12)
	v_add_f32_e32 v133, v133, v149
	s_waitcnt lgkmcnt(11)
	v_add_f32_e32 v134, v134, v150
	s_waitcnt lgkmcnt(10)
	v_add_f32_e32 v135, v135, v151
	s_waitcnt lgkmcnt(9)
	v_add_f32_e32 v136, v136, v172
	s_waitcnt lgkmcnt(8)
	v_add_f32_e32 v137, v137, v173
	s_waitcnt lgkmcnt(7)
	v_add_f32_e32 v138, v138, v174
	s_waitcnt lgkmcnt(6)
	v_add_f32_e32 v139, v139, v175
	s_waitcnt lgkmcnt(5)
	v_add_f32_e32 v140, v140, v176
	s_waitcnt lgkmcnt(4)
	v_add_f32_e32 v141, v141, v177
	s_waitcnt lgkmcnt(3)
	v_add_f32_e32 v142, v142, v178
	s_waitcnt lgkmcnt(2)
	v_add_f32_e32 v143, v143, v179
	s_waitcnt lgkmcnt(1)
	v_add_f32_e32 v144, v144, v180
	s_waitcnt lgkmcnt(0)
	v_add_f32_e32 v145, v145, v181
	ds_bpermute_b32 v146, v162, v130
	ds_bpermute_b32 v147, v162, v131
	ds_bpermute_b32 v148, v162, v132
	ds_bpermute_b32 v149, v162, v133
	ds_bpermute_b32 v150, v162, v134
	ds_bpermute_b32 v151, v162, v135
	ds_bpermute_b32 v172, v162, v136
	ds_bpermute_b32 v173, v162, v137
	ds_bpermute_b32 v174, v162, v138
	ds_bpermute_b32 v175, v162, v139
	ds_bpermute_b32 v176, v162, v140
	ds_bpermute_b32 v177, v162, v141
	ds_bpermute_b32 v178, v162, v142
	ds_bpermute_b32 v179, v162, v143
	ds_bpermute_b32 v180, v162, v144
	ds_bpermute_b32 v181, v162, v145
	s_waitcnt lgkmcnt(15)
	v_add_f32_e32 v130, v130, v146
	s_waitcnt lgkmcnt(14)
	v_add_f32_e32 v131, v131, v147
	s_waitcnt lgkmcnt(13)
	v_add_f32_e32 v132, v132, v148
	s_waitcnt lgkmcnt(12)
	v_add_f32_e32 v133, v133, v149
	s_waitcnt lgkmcnt(11)
	v_add_f32_e32 v134, v134, v150
	s_waitcnt lgkmcnt(10)
	v_add_f32_e32 v135, v135, v151
	s_waitcnt lgkmcnt(9)
	v_add_f32_e32 v136, v136, v172
	s_waitcnt lgkmcnt(8)
	v_add_f32_e32 v137, v137, v173
	s_waitcnt lgkmcnt(7)
	v_add_f32_e32 v138, v138, v174
	s_waitcnt lgkmcnt(6)
	v_add_f32_e32 v139, v139, v175
	s_waitcnt lgkmcnt(5)
	v_add_f32_e32 v140, v140, v176
	s_waitcnt lgkmcnt(4)
	v_add_f32_e32 v141, v141, v177
	s_waitcnt lgkmcnt(3)
	v_add_f32_e32 v142, v142, v178
	s_waitcnt lgkmcnt(2)
	v_add_f32_e32 v143, v143, v179
	s_waitcnt lgkmcnt(1)
	v_add_f32_e32 v144, v144, v180
	s_waitcnt lgkmcnt(0)
	v_add_f32_e32 v145, v145, v181
	ds_bpermute_b32 v146, v163, v130
	ds_bpermute_b32 v147, v163, v131
	ds_bpermute_b32 v148, v163, v132
	ds_bpermute_b32 v149, v163, v133
	ds_bpermute_b32 v150, v163, v134
	ds_bpermute_b32 v151, v163, v135
	ds_bpermute_b32 v172, v163, v136
	ds_bpermute_b32 v173, v163, v137
	ds_bpermute_b32 v174, v163, v138
	ds_bpermute_b32 v175, v163, v139
	ds_bpermute_b32 v176, v163, v140
	ds_bpermute_b32 v177, v163, v141
	ds_bpermute_b32 v178, v163, v142
	ds_bpermute_b32 v179, v163, v143
	ds_bpermute_b32 v180, v163, v144
	ds_bpermute_b32 v181, v163, v145
	s_waitcnt lgkmcnt(15)
	v_add_f32_e32 v130, v130, v146
	s_waitcnt lgkmcnt(14)
	v_add_f32_e32 v131, v131, v147
	s_waitcnt lgkmcnt(13)
	v_add_f32_e32 v132, v132, v148
	s_waitcnt lgkmcnt(12)
	v_add_f32_e32 v133, v133, v149
	s_waitcnt lgkmcnt(11)
	v_add_f32_e32 v134, v134, v150
	s_waitcnt lgkmcnt(10)
	v_add_f32_e32 v135, v135, v151
	s_waitcnt lgkmcnt(9)
	v_add_f32_e32 v136, v136, v172
	s_waitcnt lgkmcnt(8)
	v_add_f32_e32 v137, v137, v173
	s_waitcnt lgkmcnt(7)
	v_add_f32_e32 v138, v138, v174
	s_waitcnt lgkmcnt(6)
	v_add_f32_e32 v139, v139, v175
	s_waitcnt lgkmcnt(5)
	v_add_f32_e32 v140, v140, v176
	s_waitcnt lgkmcnt(4)
	v_add_f32_e32 v141, v141, v177
	s_waitcnt lgkmcnt(3)
	v_add_f32_e32 v142, v142, v178
	s_waitcnt lgkmcnt(2)
	v_add_f32_e32 v143, v143, v179
	s_waitcnt lgkmcnt(1)
	v_add_f32_e32 v144, v144, v180
	s_waitcnt lgkmcnt(0)
	v_add_f32_e32 v145, v145, v181
	ds_bpermute_b32 v146, v164, v130
	ds_bpermute_b32 v147, v164, v131
	ds_bpermute_b32 v148, v164, v132
	ds_bpermute_b32 v149, v164, v133
	ds_bpermute_b32 v150, v164, v134
	ds_bpermute_b32 v151, v164, v135
	ds_bpermute_b32 v172, v164, v136
	ds_bpermute_b32 v173, v164, v137
	ds_bpermute_b32 v174, v164, v138
	ds_bpermute_b32 v175, v164, v139
	ds_bpermute_b32 v176, v164, v140
	ds_bpermute_b32 v177, v164, v141
	ds_bpermute_b32 v178, v164, v142
	ds_bpermute_b32 v179, v164, v143
	ds_bpermute_b32 v180, v164, v144
	ds_bpermute_b32 v181, v164, v145
	s_waitcnt lgkmcnt(15)
	v_add_f32_e32 v130, v130, v146
	s_waitcnt lgkmcnt(14)
	v_add_f32_e32 v131, v131, v147
	s_waitcnt lgkmcnt(13)
	v_add_f32_e32 v132, v132, v148
	s_waitcnt lgkmcnt(12)
	v_add_f32_e32 v133, v133, v149
	s_waitcnt lgkmcnt(11)
	v_add_f32_e32 v134, v134, v150
	s_waitcnt lgkmcnt(10)
	v_add_f32_e32 v135, v135, v151
	s_waitcnt lgkmcnt(9)
	v_add_f32_e32 v136, v136, v172
	s_waitcnt lgkmcnt(8)
	v_add_f32_e32 v137, v137, v173
	s_waitcnt lgkmcnt(7)
	v_add_f32_e32 v138, v138, v174
	s_waitcnt lgkmcnt(6)
	v_add_f32_e32 v139, v139, v175
	s_waitcnt lgkmcnt(5)
	v_add_f32_e32 v140, v140, v176
	s_waitcnt lgkmcnt(4)
	v_add_f32_e32 v141, v141, v177
	s_waitcnt lgkmcnt(3)
	v_add_f32_e32 v142, v142, v178
	s_waitcnt lgkmcnt(2)
	v_add_f32_e32 v143, v143, v179
	s_waitcnt lgkmcnt(1)
	v_add_f32_e32 v144, v144, v180
	s_waitcnt lgkmcnt(0)
	v_add_f32_e32 v145, v145, v181
	ds_bpermute_b32 v146, v165, v130
	ds_bpermute_b32 v147, v165, v131
	ds_bpermute_b32 v148, v165, v132
	ds_bpermute_b32 v149, v165, v133
	ds_bpermute_b32 v150, v165, v134
	ds_bpermute_b32 v151, v165, v135
	ds_bpermute_b32 v172, v165, v136
	ds_bpermute_b32 v173, v165, v137
	ds_bpermute_b32 v174, v165, v138
	ds_bpermute_b32 v175, v165, v139
	ds_bpermute_b32 v176, v165, v140
	ds_bpermute_b32 v177, v165, v141
	ds_bpermute_b32 v178, v165, v142
	ds_bpermute_b32 v179, v165, v143
	ds_bpermute_b32 v180, v165, v144
	ds_bpermute_b32 v181, v165, v145
	s_waitcnt lgkmcnt(15)
	v_add_f32_e32 v130, v130, v146
	s_waitcnt lgkmcnt(14)
	v_add_f32_e32 v131, v131, v147
	s_waitcnt lgkmcnt(13)
	v_add_f32_e32 v132, v132, v148
	s_waitcnt lgkmcnt(12)
	v_add_f32_e32 v133, v133, v149
	s_waitcnt lgkmcnt(11)
	v_add_f32_e32 v134, v134, v150
	s_waitcnt lgkmcnt(10)
	v_add_f32_e32 v135, v135, v151
	s_waitcnt lgkmcnt(9)
	v_add_f32_e32 v136, v136, v172
	s_waitcnt lgkmcnt(8)
	v_add_f32_e32 v137, v137, v173
	s_waitcnt lgkmcnt(7)
	v_add_f32_e32 v138, v138, v174
	s_waitcnt lgkmcnt(6)
	v_add_f32_e32 v139, v139, v175
	s_waitcnt lgkmcnt(5)
	v_add_f32_e32 v140, v140, v176
	s_waitcnt lgkmcnt(4)
	v_add_f32_e32 v141, v141, v177
	s_waitcnt lgkmcnt(3)
	v_add_f32_e32 v142, v142, v178
	s_waitcnt lgkmcnt(2)
	v_add_f32_e32 v143, v143, v179
	s_waitcnt lgkmcnt(1)
	v_add_f32_e32 v144, v144, v180
	s_waitcnt lgkmcnt(0)
	v_add_f32_e32 v145, v145, v181
	v_fmamk_f32 v130, v130, 0x3c000000, v153
	v_fmamk_f32 v131, v131, 0x3c000000, v153
	v_fmamk_f32 v132, v132, 0x3c000000, v153
	v_fmamk_f32 v133, v133, 0x3c000000, v153
	v_fmamk_f32 v134, v134, 0x3c000000, v153
	v_fmamk_f32 v135, v135, 0x3c000000, v153
	v_fmamk_f32 v136, v136, 0x3c000000, v153
	v_fmamk_f32 v137, v137, 0x3c000000, v153
	v_fmamk_f32 v138, v138, 0x3c000000, v153
	v_fmamk_f32 v139, v139, 0x3c000000, v153
	v_fmamk_f32 v140, v140, 0x3c000000, v153
	v_fmamk_f32 v141, v141, 0x3c000000, v153
	v_fmamk_f32 v142, v142, 0x3c000000, v153
	v_fmamk_f32 v143, v143, 0x3c000000, v153
	v_fmamk_f32 v144, v144, 0x3c000000, v153
	v_fmamk_f32 v145, v145, 0x3c000000, v153
	v_rsq_f32_e32 v130, v130
	v_rsq_f32_e32 v131, v131
	v_rsq_f32_e32 v132, v132
	v_rsq_f32_e32 v133, v133
	v_rsq_f32_e32 v134, v134
	v_rsq_f32_e32 v135, v135
	v_rsq_f32_e32 v136, v136
	v_rsq_f32_e32 v137, v137
	v_rsq_f32_e32 v138, v138
	v_rsq_f32_e32 v139, v139
	v_rsq_f32_e32 v140, v140
	v_rsq_f32_e32 v141, v141
	v_rsq_f32_e32 v142, v142
	v_rsq_f32_e32 v143, v143
	v_rsq_f32_e32 v144, v144
	v_rsq_f32_e32 v145, v145
	v_lshlrev_b32_e32 v190, 1, v171
	v_mul_u32_u24_e32 v191, 0x440, v170
	v_add3_u32 v190, s34, v190, v191
	v_mul_f32_e32 v182, v60, v130
	v_bfe_u32 v186, v182, 16, 1
	v_add3_u32 v182, v182, v186, s81
	ds_write_b16_d16_hi v190, v182
	v_mul_f32_e32 v183, v62, v130
	v_bfe_u32 v187, v183, 16, 1
	v_add3_u32 v183, v183, v187, s81
	ds_write_b16_d16_hi v190, v183 offset:64
	v_mul_f32_e32 v184, v74, v130
	v_bfe_u32 v188, v184, 16, 1
	v_add3_u32 v184, v184, v188, s81
	ds_write_b16_d16_hi v190, v184 offset:128
	v_mul_f32_e32 v185, v72, v130
	v_bfe_u32 v189, v185, 16, 1
	v_add3_u32 v185, v185, v189, s81
	ds_write_b16_d16_hi v190, v185 offset:192
	v_mul_f32_e32 v182, v55, v131
	v_bfe_u32 v186, v182, 16, 1
	v_add3_u32 v182, v182, v186, s81
	ds_write_b16_d16_hi v190, v182 offset:272
	v_mul_f32_e32 v183, v57, v131
	v_bfe_u32 v187, v183, 16, 1
	v_add3_u32 v183, v183, v187, s81
	ds_write_b16_d16_hi v190, v183 offset:336
	v_mul_f32_e32 v184, v59, v131
	v_bfe_u32 v188, v184, 16, 1
	v_add3_u32 v184, v184, v188, s81
	ds_write_b16_d16_hi v190, v184 offset:400
	v_mul_f32_e32 v185, v61, v131
	v_bfe_u32 v189, v185, 16, 1
	v_add3_u32 v185, v185, v189, s81
	ds_write_b16_d16_hi v190, v185 offset:464
	v_mul_f32_e32 v182, v52, v132
	v_bfe_u32 v186, v182, 16, 1
	v_add3_u32 v182, v182, v186, s81
	ds_write_b16_d16_hi v190, v182 offset:544
	v_mul_f32_e32 v183, v54, v132
	v_bfe_u32 v187, v183, 16, 1
	v_add3_u32 v183, v183, v187, s81
	ds_write_b16_d16_hi v190, v183 offset:608
	v_mul_f32_e32 v184, v56, v132
	v_bfe_u32 v188, v184, 16, 1
	v_add3_u32 v184, v184, v188, s81
	ds_write_b16_d16_hi v190, v184 offset:672
	v_mul_f32_e32 v185, v58, v132
	v_bfe_u32 v189, v185, 16, 1
	v_add3_u32 v185, v185, v189, s81
	ds_write_b16_d16_hi v190, v185 offset:736
	v_mul_f32_e32 v182, v47, v133
	v_bfe_u32 v186, v182, 16, 1
	v_add3_u32 v182, v182, v186, s81
	ds_write_b16_d16_hi v190, v182 offset:816
	v_mul_f32_e32 v183, v49, v133
	v_bfe_u32 v187, v183, 16, 1
	v_add3_u32 v183, v183, v187, s81
	ds_write_b16_d16_hi v190, v183 offset:880
	v_mul_f32_e32 v184, v51, v133
	v_bfe_u32 v188, v184, 16, 1
	v_add3_u32 v184, v184, v188, s81
	ds_write_b16_d16_hi v190, v184 offset:944
	v_mul_f32_e32 v185, v53, v133
	v_bfe_u32 v189, v185, 16, 1
	v_add3_u32 v185, v185, v189, s81
	ds_write_b16_d16_hi v190, v185 offset:1008
	v_mul_f32_e32 v182, v44, v134
	v_bfe_u32 v186, v182, 16, 1
	v_add3_u32 v182, v182, v186, s81
	ds_write_b16_d16_hi v190, v182 offset:2176
	v_mul_f32_e32 v183, v46, v134
	v_bfe_u32 v187, v183, 16, 1
	v_add3_u32 v183, v183, v187, s81
	ds_write_b16_d16_hi v190, v183 offset:2240
	v_mul_f32_e32 v184, v48, v134
	v_bfe_u32 v188, v184, 16, 1
	v_add3_u32 v184, v184, v188, s81
	ds_write_b16_d16_hi v190, v184 offset:2304
	v_mul_f32_e32 v185, v50, v134
	v_bfe_u32 v189, v185, 16, 1
	v_add3_u32 v185, v185, v189, s81
	ds_write_b16_d16_hi v190, v185 offset:2368
	v_mul_f32_e32 v182, v39, v135
	v_bfe_u32 v186, v182, 16, 1
	v_add3_u32 v182, v182, v186, s81
	ds_write_b16_d16_hi v190, v182 offset:2448
	v_mul_f32_e32 v183, v41, v135
	v_bfe_u32 v187, v183, 16, 1
	v_add3_u32 v183, v183, v187, s81
	ds_write_b16_d16_hi v190, v183 offset:2512
	v_mul_f32_e32 v184, v43, v135
	v_bfe_u32 v188, v184, 16, 1
	v_add3_u32 v184, v184, v188, s81
	ds_write_b16_d16_hi v190, v184 offset:2576
	v_mul_f32_e32 v185, v45, v135
	v_bfe_u32 v189, v185, 16, 1
	v_add3_u32 v185, v185, v189, s81
	ds_write_b16_d16_hi v190, v185 offset:2640
	v_mul_f32_e32 v182, v36, v136
	v_bfe_u32 v186, v182, 16, 1
	v_add3_u32 v182, v182, v186, s81
	ds_write_b16_d16_hi v190, v182 offset:2720
	v_mul_f32_e32 v183, v38, v136
	v_bfe_u32 v187, v183, 16, 1
	v_add3_u32 v183, v183, v187, s81
	ds_write_b16_d16_hi v190, v183 offset:2784
	v_mul_f32_e32 v184, v40, v136
	v_bfe_u32 v188, v184, 16, 1
	v_add3_u32 v184, v184, v188, s81
	ds_write_b16_d16_hi v190, v184 offset:2848
	v_mul_f32_e32 v185, v42, v136
	v_bfe_u32 v189, v185, 16, 1
	v_add3_u32 v185, v185, v189, s81
	ds_write_b16_d16_hi v190, v185 offset:2912
	v_mul_f32_e32 v182, v31, v137
	v_bfe_u32 v186, v182, 16, 1
	v_add3_u32 v182, v182, v186, s81
	ds_write_b16_d16_hi v190, v182 offset:2992
	v_mul_f32_e32 v183, v34, v137
	v_bfe_u32 v187, v183, 16, 1
	v_add3_u32 v183, v183, v187, s81
	ds_write_b16_d16_hi v190, v183 offset:3056
	v_mul_f32_e32 v184, v35, v137
	v_bfe_u32 v188, v184, 16, 1
	v_add3_u32 v184, v184, v188, s81
	ds_write_b16_d16_hi v190, v184 offset:3120
	v_mul_f32_e32 v185, v37, v137
	v_bfe_u32 v189, v185, 16, 1
	v_add3_u32 v185, v185, v189, s81
	ds_write_b16_d16_hi v190, v185 offset:3184
	v_mul_f32_e32 v182, v28, v138
	v_bfe_u32 v186, v182, 16, 1
	v_add3_u32 v182, v182, v186, s81
	ds_write_b16_d16_hi v190, v182 offset:4352
	v_mul_f32_e32 v183, v30, v138
	v_bfe_u32 v187, v183, 16, 1
	v_add3_u32 v183, v183, v187, s81
	ds_write_b16_d16_hi v190, v183 offset:4416
	v_mul_f32_e32 v184, v32, v138
	v_bfe_u32 v188, v184, 16, 1
	v_add3_u32 v184, v184, v188, s81
	ds_write_b16_d16_hi v190, v184 offset:4480
	v_mul_f32_e32 v185, v33, v138
	v_bfe_u32 v189, v185, 16, 1
	v_add3_u32 v185, v185, v189, s81
	ds_write_b16_d16_hi v190, v185 offset:4544
	v_mul_f32_e32 v182, v23, v139
	v_bfe_u32 v186, v182, 16, 1
	v_add3_u32 v182, v182, v186, s81
	ds_write_b16_d16_hi v190, v182 offset:4624
	v_mul_f32_e32 v183, v26, v139
	v_bfe_u32 v187, v183, 16, 1
	v_add3_u32 v183, v183, v187, s81
	ds_write_b16_d16_hi v190, v183 offset:4688
	v_mul_f32_e32 v184, v27, v139
	v_bfe_u32 v188, v184, 16, 1
	v_add3_u32 v184, v184, v188, s81
	ds_write_b16_d16_hi v190, v184 offset:4752
	v_mul_f32_e32 v185, v29, v139
	v_bfe_u32 v189, v185, 16, 1
	v_add3_u32 v185, v185, v189, s81
	ds_write_b16_d16_hi v190, v185 offset:4816
	v_mul_f32_e32 v182, v20, v140
	v_bfe_u32 v186, v182, 16, 1
	v_add3_u32 v182, v182, v186, s81
	ds_write_b16_d16_hi v190, v182 offset:4896
	v_mul_f32_e32 v183, v22, v140
	v_bfe_u32 v187, v183, 16, 1
	v_add3_u32 v183, v183, v187, s81
	ds_write_b16_d16_hi v190, v183 offset:4960
	v_mul_f32_e32 v184, v24, v140
	v_bfe_u32 v188, v184, 16, 1
	v_add3_u32 v184, v184, v188, s81
	ds_write_b16_d16_hi v190, v184 offset:5024
	v_mul_f32_e32 v185, v25, v140
	v_bfe_u32 v189, v185, 16, 1
	v_add3_u32 v185, v185, v189, s81
	ds_write_b16_d16_hi v190, v185 offset:5088
	v_mul_f32_e32 v182, v15, v141
	v_bfe_u32 v186, v182, 16, 1
	v_add3_u32 v182, v182, v186, s81
	ds_write_b16_d16_hi v190, v182 offset:5168
	v_mul_f32_e32 v183, v18, v141
	v_bfe_u32 v187, v183, 16, 1
	v_add3_u32 v183, v183, v187, s81
	ds_write_b16_d16_hi v190, v183 offset:5232
	v_mul_f32_e32 v184, v19, v141
	v_bfe_u32 v188, v184, 16, 1
	v_add3_u32 v184, v184, v188, s81
	ds_write_b16_d16_hi v190, v184 offset:5296
	v_mul_f32_e32 v185, v21, v141
	v_bfe_u32 v189, v185, 16, 1
	v_add3_u32 v185, v185, v189, s81
	ds_write_b16_d16_hi v190, v185 offset:5360
	v_mul_f32_e32 v182, v12, v142
	v_bfe_u32 v186, v182, 16, 1
	v_add3_u32 v182, v182, v186, s81
	ds_write_b16_d16_hi v190, v182 offset:6528
	v_mul_f32_e32 v183, v14, v142
	v_bfe_u32 v187, v183, 16, 1
	v_add3_u32 v183, v183, v187, s81
	ds_write_b16_d16_hi v190, v183 offset:6592
	v_mul_f32_e32 v184, v16, v142
	v_bfe_u32 v188, v184, 16, 1
	v_add3_u32 v184, v184, v188, s81
	ds_write_b16_d16_hi v190, v184 offset:6656
	v_mul_f32_e32 v185, v17, v142
	v_bfe_u32 v189, v185, 16, 1
	v_add3_u32 v185, v185, v189, s81
	ds_write_b16_d16_hi v190, v185 offset:6720
	v_mul_f32_e32 v182, v6, v143
	v_bfe_u32 v186, v182, 16, 1
	v_add3_u32 v182, v182, v186, s81
	ds_write_b16_d16_hi v190, v182 offset:6800
	v_mul_f32_e32 v183, v10, v143
	v_bfe_u32 v187, v183, 16, 1
	v_add3_u32 v183, v183, v187, s81
	ds_write_b16_d16_hi v190, v183 offset:6864
	v_mul_f32_e32 v184, v11, v143
	v_bfe_u32 v188, v184, 16, 1
	v_add3_u32 v184, v184, v188, s81
	ds_write_b16_d16_hi v190, v184 offset:6928
	v_mul_f32_e32 v185, v13, v143
	v_bfe_u32 v189, v185, 16, 1
	v_add3_u32 v185, v185, v189, s81
	ds_write_b16_d16_hi v190, v185 offset:6992
	v_mul_f32_e32 v182, v3, v144
	v_bfe_u32 v186, v182, 16, 1
	v_add3_u32 v182, v182, v186, s81
	ds_write_b16_d16_hi v190, v182 offset:7072
	v_mul_f32_e32 v183, v5, v144
	v_bfe_u32 v187, v183, 16, 1
	v_add3_u32 v183, v183, v187, s81
	ds_write_b16_d16_hi v190, v183 offset:7136
	v_mul_f32_e32 v184, v7, v144
	v_bfe_u32 v188, v184, 16, 1
	v_add3_u32 v184, v184, v188, s81
	ds_write_b16_d16_hi v190, v184 offset:7200
	v_mul_f32_e32 v185, v9, v144
	v_bfe_u32 v189, v185, 16, 1
	v_add3_u32 v185, v185, v189, s81
	ds_write_b16_d16_hi v190, v185 offset:7264
	v_mul_f32_e32 v182, v0, v145
	v_bfe_u32 v186, v182, 16, 1
	v_add3_u32 v182, v182, v186, s81
	ds_write_b16_d16_hi v190, v182 offset:7344
	v_mul_f32_e32 v183, v1, v145
	v_bfe_u32 v187, v183, 16, 1
	v_add3_u32 v183, v183, v187, s81
	ds_write_b16_d16_hi v190, v183 offset:7408
	v_mul_f32_e32 v184, v2, v145
	v_bfe_u32 v188, v184, 16, 1
	v_add3_u32 v184, v184, v188, s81
	ds_write_b16_d16_hi v190, v184 offset:7472
	v_mul_f32_e32 v185, v4, v145
	v_bfe_u32 v189, v185, 16, 1
	v_add3_u32 v185, v185, v189, s81
	ds_write_b16_d16_hi v190, v185 offset:7536
	s_or_b32 s0, s40, s99
	s_mov_b32 s1, s41
	s_lshl_b64 s[0:1], s[0:1], 11
	v_lshlrev_b32_e32 v0, 1, v169
	v_lshrrev_b32_e32 v6, 4, v168
	v_and_b32_e32 v96, 0xf0, v0
	v_mul_u32_u24_e32 v0, 0x110, v6
	s_add_u32 s0, s92, s0
	v_add3_u32 v8, s34, v96, v0
	s_addc_u32 s1, s93, s1
	s_lshl_b32 s35, s98, 8
	s_add_u32 s0, s0, s35
	s_addc_u32 s1, s1, 0
	s_waitcnt lgkmcnt(0)
	ds_read_b128 v[132:135], v8
	ds_read_b128 v[136:139], v8 offset:1088
	ds_read_b128 v[140:143], v8 offset:2176
	ds_read_b128 v[144:147], v8 offset:3264
	ds_read_b128 v[148:151], v8 offset:4352
	ds_read_b128 v[172:175], v8 offset:5440
	ds_read_b128 v[176:179], v8 offset:6528
	ds_read_b128 v[180:183], v8 offset:7616
	v_lshl_add_u64 v[4:5], s[0:1], 0, v[96:97]
	v_lshlrev_b32_e32 v96, 11, v6
	v_lshl_add_u64 v[6:7], v[4:5], 0, v[96:97]
	s_waitcnt lgkmcnt(7)
	global_store_dwordx4 v[6:7], v[132:135], off nt
	v_or_b32_e32 v6, 0x2000, v96
	v_mov_b32_e32 v7, v97
	v_lshl_add_u64 v[6:7], v[4:5], 0, v[6:7]
	s_waitcnt lgkmcnt(6)
	global_store_dwordx4 v[6:7], v[136:139], off nt
	v_or_b32_e32 v6, 0x4000, v96
	v_mov_b32_e32 v7, v97
	v_lshl_add_u64 v[6:7], v[4:5], 0, v[6:7]
	s_waitcnt lgkmcnt(5)
	global_store_dwordx4 v[6:7], v[140:143], off nt
	v_or_b32_e32 v6, 0x6000, v96
	v_mov_b32_e32 v7, v97
	v_lshl_add_u64 v[6:7], v[4:5], 0, v[6:7]
	s_waitcnt lgkmcnt(4)
	global_store_dwordx4 v[6:7], v[144:147], off nt
	v_or_b32_e32 v6, 0x8000, v96
	v_mov_b32_e32 v7, v97
	v_lshl_add_u64 v[6:7], v[4:5], 0, v[6:7]
	s_waitcnt lgkmcnt(3)
	global_store_dwordx4 v[6:7], v[148:151], off nt
	v_or_b32_e32 v6, 0xa000, v96
	v_mov_b32_e32 v7, v97
	v_lshl_add_u64 v[6:7], v[4:5], 0, v[6:7]
	s_waitcnt lgkmcnt(2)
	global_store_dwordx4 v[6:7], v[172:175], off nt
	v_or_b32_e32 v6, 0xc000, v96
	v_mov_b32_e32 v7, v97
	v_lshl_add_u64 v[6:7], v[4:5], 0, v[6:7]
	s_waitcnt lgkmcnt(1)
	global_store_dwordx4 v[6:7], v[176:179], off nt
	v_or_b32_e32 v96, 0xe000, v96
	v_lshl_add_u64 v[4:5], v[4:5], 0, v[96:97]
	s_waitcnt lgkmcnt(0)
	global_store_dwordx4 v[4:5], v[180:183], off nt
	s_branch .LBB0_275
